# speedup vs baseline: 1.0042x; 1.0042x over previous
; DEVINL u16 f2bf(float f) { uint32_t u = __float_as_uint(f); u += 0x7FFFu + ((u >> 16) & 1u); return (u16)(u >> 16); }
; DEVINL void phase_prep(const Params& p, int layer, char* smem, int wv) {
;     ...
;   for (int item = blockIdx.x; item < nW + nX; item += gridDim.x) {
;     if (item < nIn) {
;       int nt = item / 16, kt = item % 16;
;       transpose_tile(p.w_in + (size_t)layer * DM * INW, INW, (u16*)(ws + OFF_WIN), DM, nt * 256, kt * 128, p.g_mix + layer * DM, true, smem, wv);
;     } else if (item < nIn + nOut) {
;       int it = item - nIn; int nt = it / 16, kt = it % 16;
;       transpose_tile(p.w_out + (size_t)layer * DM * DM, DM, (u16*)(ws + OFF_WOUT), DM, nt * 256, kt * 128, nullptr, false, smem, wv);
;     } else if (item < nIn + nOut + nUp) {
;       int it = item - nIn - nOut; int nt = it / 16, kt = it % 16;
;       transpose_tile(p.w_up + (size_t)layer * DM * DFF, DFF, (u16*)(ws + OFF_WUP), DM, nt * 256, kt * 128, p.g_mlp + layer * DM, false, smem, wv);
;     } else if (item < nW) {
;       int it = item - nIn - nOut - nUp; int nt = it / 64, kt = it % 64;
;       transpose_tile(p.w_down + (size_t)layer * DFF * DM, DM, (u16*)(ws + OFF_WDOWN), DFF, nt * 256, kt * 128, nullptr, false, smem, wv);
;     } else {
;       int r = (item - nW) * 8 + wid;
;       const float4* xr = (const float4*)(p.x + (size_t)r * DM);
;       u16* xb = (u16*)(ws + OFF_XB) + (size_t)r * DM;
;       float ss = 0.f;
; #pragma unroll
;       for (int i = 0; i < 8; ++i) {
;         float4 v = xr[i * 64 + lane];
;         ss += v.x * v.x + v.y * v.y + v.z * v.z + v.w * v.w;
;         bf16x4 o; o[0] = (short)f2bf(v.x); o[1] = (short)f2bf(v.y); o[2] = (short)f2bf(v.z); o[3] = (short)f2bf(v.w);
;         *(bf16x4*)(xb + (i * 64 + lane) * 4) = o;
;       }
.LBB0_26:
	s_cmpk_gt_i32 s38, 0x16f
	s_mov_b64 s[4:5], -1
	s_cbranch_scc0 .LBB0_44
	s_cmpk_gt_u32 s38, 0x1ef
	s_cbranch_scc0 .LBB0_41
	s_cmpk_gt_u32 s38, 0x3ef
	s_cbranch_scc0 .LBB0_36
	s_cmpk_gt_u32 s38, 0x5ef
	s_cbranch_scc0 .LBB0_33
	v_lshl_add_u32 v32, s38, 3, v1
	v_ashrrev_i32_e32 v33, 31, v32
	v_readlane_b32 s60, v254, 2
	v_lshlrev_b64 v[34:35], 13, v[32:33]
	v_readlane_b32 s61, v254, 3
	v_mov_b32_e32 v7, v3
	v_mov_b32_e32 v9, v3
	v_lshl_add_u64 v[64:65], s[60:61], 0, v[34:35]
	v_lshl_add_u64 v[48:49], v[64:65], 0, v[6:7]
	global_load_dwordx4 v[128:131], v[48:49], off
	v_lshlrev_b64 v[34:35], 12, v[32:33]
	v_lshl_add_u64 v[34:35], s[10:11], 0, v[34:35]
	v_lshl_add_u64 v[40:41], v[34:35], 0, v[8:9]
	v_mov_b32_e32 v13, v3
	v_lshl_add_u64 v[50:51], v[34:35], 0, v[12:13]
	v_mov_b32_e32 v15, v3
	v_mov_b32_e32 v17, v3
	v_lshl_add_u64 v[54:55], v[64:65], 0, v[16:17]
	v_mov_b32_e32 v19, v3
	v_mov_b32_e32 v21, v3
	v_lshl_add_u64 v[58:59], v[64:65], 0, v[20:21]
	v_mov_b32_e32 v23, v3
	v_mov_b32_e32 v25, v3
	v_lshl_add_u64 v[62:63], v[64:65], 0, v[24:25]
	v_mov_b32_e32 v27, v3
	v_mov_b32_e32 v29, v3
	v_lshl_add_u64 v[64:65], v[64:65], 0, v[28:29]
	global_load_dwordx4 v[132:135], v[48:49], off offset:1024
	global_load_dwordx4 v[136:139], v[48:49], off offset:2048
	global_load_dwordx4 v[140:143], v[48:49], off offset:3072
	global_load_dwordx4 v[144:147], v[54:55], off
	global_load_dwordx4 v[148:151], v[58:59], off
	global_load_dwordx4 v[152:155], v[62:63], off
	global_load_dwordx4 v[156:159], v[64:65], off
	v_mov_b32_e32 v31, v3
	v_readlane_b32 s62, v254, 4
	v_readlane_b32 s63, v254, 5
	v_readlane_b32 s64, v254, 6
	v_readlane_b32 s65, v254, 7
	v_readlane_b32 s66, v254, 8
	v_readlane_b32 s67, v254, 9
	v_readlane_b32 s68, v254, 10
	v_readlane_b32 s69, v254, 11
	v_readlane_b32 s70, v254, 12
	v_readlane_b32 s71, v254, 13
	v_readlane_b32 s72, v254, 14
	v_readlane_b32 s73, v254, 15
	v_readlane_b32 s74, v254, 16
	v_readlane_b32 s75, v254, 17
	s_waitcnt vmcnt(7)
	v_bfe_u32 v2, v131, 16, 1
	v_bfe_u32 v7, v130, 16, 1
	v_bfe_u32 v9, v129, 16, 1
	v_bfe_u32 v11, v128, 16, 1
	v_add3_u32 v11, v128, v11, s26
	v_add3_u32 v9, v129, v9, s26
	v_add3_u32 v7, v130, v7, s26
	v_add3_u32 v2, v131, v2, s26
	v_perm_b32 v43, v2, v7, s27
	v_perm_b32 v42, v9, v11, s27
	global_store_dwordx2 v[40:41], v[42:43], off
	v_mov_b32_e32 v11, v3
	v_lshl_add_u64 v[44:45], v[34:35], 0, v[10:11]
	v_pk_mul_f32 v[36:37], v[128:129], v[128:129]
	v_pk_mul_f32 v[38:39], v[130:131], v[130:131]
	s_waitcnt vmcnt(7)
	v_bfe_u32 v2, v135, 16, 1
	v_bfe_u32 v7, v134, 16, 1
	v_bfe_u32 v9, v133, 16, 1
	v_bfe_u32 v11, v132, 16, 1
	v_add3_u32 v11, v132, v11, s26
	v_add3_u32 v9, v133, v9, s26
	v_add3_u32 v7, v134, v7, s26
	v_add3_u32 v2, v135, v2, s26
	v_perm_b32 v47, v2, v7, s27
	v_perm_b32 v46, v9, v11, s27
	global_store_dwordx2 v[44:45], v[46:47], off
	s_waitcnt vmcnt(7)
	v_bfe_u32 v2, v139, 16, 1
	v_bfe_u32 v7, v138, 16, 1
	v_bfe_u32 v9, v137, 16, 1
	v_bfe_u32 v11, v136, 16, 1
	v_add3_u32 v11, v136, v11, s26
	v_add3_u32 v9, v137, v9, s26
	v_add3_u32 v7, v138, v7, s26
	v_add3_u32 v2, v139, v2, s26
	v_perm_b32 v53, v2, v7, s27
	v_perm_b32 v52, v9, v11, s27
	global_store_dwordx2 v[50:51], v[52:53], off
	v_lshl_add_u64 v[52:53], v[34:35], 0, v[14:15]
	s_waitcnt vmcnt(7)
	v_bfe_u32 v2, v143, 16, 1
	v_bfe_u32 v7, v142, 16, 1
	v_bfe_u32 v9, v141, 16, 1
	v_bfe_u32 v11, v140, 16, 1
	v_add3_u32 v11, v140, v11, s26
	v_add3_u32 v9, v141, v9, s26
	v_add3_u32 v7, v142, v7, s26
	v_add3_u32 v2, v143, v2, s26
	v_perm_b32 v57, v2, v7, s27
	v_perm_b32 v56, v9, v11, s27
	global_store_dwordx2 v[52:53], v[56:57], off
	v_lshl_add_u64 v[56:57], v[34:35], 0, v[18:19]
	s_waitcnt vmcnt(7)
; DEVINL u16 f2bf(float f) { uint32_t u = __float_as_uint(f); u += 0x7FFFu + ((u >> 16) & 1u); return (u16)(u >> 16); }
; DEVINL float shx(float v, int m, int lane) { return __int_as_float(__builtin_amdgcn_ds_bpermute((lane ^ m) << 2, __float_as_int(v))); }
; DEVINL void phase_prep(const Params& p, int layer, char* smem, int wv) {
;     ...
;       for (int i = 0; i < 8; ++i) {
;         float4 v = xr[i * 64 + lane];
;         ss += v.x * v.x + v.y * v.y + v.z * v.z + v.w * v.w;
;         bf16x4 o; o[0] = (short)f2bf(v.x); o[1] = (short)f2bf(v.y); o[2] = (short)f2bf(v.z); o[3] = (short)f2bf(v.w);
;         *(bf16x4*)(xb + (i * 64 + lane) * 4) = o;
;       }
; #pragma unroll
;       for (int off = 32; off >= 1; off >>= 1) ss += shx(ss, off, lane);
;       float* part = (float*)(ws + OFF_PART) + (size_t)r * 32;
;       if (lane < 32) part[lane] = (lane == 0) ? ss : 0.f;
	v_bfe_u32 v2, v147, 16, 1
	v_bfe_u32 v7, v146, 16, 1
	v_bfe_u32 v9, v145, 16, 1
	v_bfe_u32 v11, v144, 16, 1
	v_add3_u32 v11, v144, v11, s26
	v_add3_u32 v9, v145, v9, s26
	v_add3_u32 v7, v146, v7, s26
	v_add3_u32 v2, v147, v2, s26
	v_perm_b32 v61, v2, v7, s27
	v_perm_b32 v60, v9, v11, s27
	global_store_dwordx2 v[56:57], v[60:61], off
	v_lshl_add_u64 v[60:61], v[34:35], 0, v[22:23]
	s_waitcnt vmcnt(7)
	v_bfe_u32 v2, v151, 16, 1
	v_bfe_u32 v7, v150, 16, 1
	v_bfe_u32 v9, v149, 16, 1
	v_bfe_u32 v11, v148, 16, 1
	v_add3_u32 v11, v148, v11, s26
	v_add3_u32 v9, v149, v9, s26
	v_add3_u32 v7, v150, v7, s26
	v_add3_u32 v2, v151, v2, s26
	v_perm_b32 v67, v2, v7, s27
	v_perm_b32 v66, v9, v11, s27
	global_store_dwordx2 v[60:61], v[66:67], off
	v_lshl_add_u64 v[66:67], v[34:35], 0, v[26:27]
	v_lshl_add_u64 v[34:35], v[34:35], 0, v[30:31]
	s_waitcnt vmcnt(7)
	v_bfe_u32 v2, v155, 16, 1
	v_bfe_u32 v7, v154, 16, 1
	v_bfe_u32 v9, v153, 16, 1
	v_bfe_u32 v11, v152, 16, 1
	v_add3_u32 v11, v152, v11, s26
	v_add3_u32 v9, v153, v9, s26
	v_add3_u32 v7, v154, v7, s26
	v_add3_u32 v2, v155, v2, s26
	v_perm_b32 v69, v2, v7, s27
	v_perm_b32 v68, v9, v11, s27
	global_store_dwordx2 v[66:67], v[68:69], off
	v_add_f32_e32 v2, v36, v37
	v_add_f32_e32 v2, v2, v38
	v_pk_mul_f32 v[36:37], v[132:133], v[132:133]
	v_add_f32_e32 v2, v2, v39
	v_pk_mul_f32 v[38:39], v[134:135], v[134:135]
	v_add_f32_e32 v7, v36, v37
	v_add_f32_e32 v7, v7, v38
	v_add_f32_e32 v7, v7, v39
	v_pk_mul_f32 v[36:37], v[136:137], v[136:137]
	v_add_f32_e32 v2, v2, v7
	v_pk_mul_f32 v[38:39], v[138:139], v[138:139]
	v_add_f32_e32 v7, v36, v37
	v_add_f32_e32 v7, v7, v38
	v_add_f32_e32 v7, v7, v39
	v_pk_mul_f32 v[36:37], v[140:141], v[140:141]
	v_add_f32_e32 v2, v2, v7
	v_pk_mul_f32 v[38:39], v[142:143], v[142:143]
	v_add_f32_e32 v7, v36, v37
	v_add_f32_e32 v7, v7, v38
	v_add_f32_e32 v7, v7, v39
	v_pk_mul_f32 v[36:37], v[144:145], v[144:145]
	v_add_f32_e32 v2, v2, v7
	v_pk_mul_f32 v[38:39], v[146:147], v[146:147]
	v_add_f32_e32 v7, v36, v37
	v_add_f32_e32 v7, v7, v38
	v_add_f32_e32 v7, v7, v39
	v_pk_mul_f32 v[36:37], v[148:149], v[148:149]
	v_add_f32_e32 v2, v2, v7
	v_pk_mul_f32 v[38:39], v[150:151], v[150:151]
	v_add_f32_e32 v7, v36, v37
	v_add_f32_e32 v7, v7, v38
	v_add_f32_e32 v7, v7, v39
	v_pk_mul_f32 v[36:37], v[152:153], v[152:153]
	v_add_f32_e32 v2, v2, v7
	v_pk_mul_f32 v[38:39], v[154:155], v[154:155]
	v_add_f32_e32 v7, v36, v37
	v_add_f32_e32 v7, v7, v38
	v_add_f32_e32 v7, v7, v39
	v_add_f32_e32 v2, v2, v7
	s_waitcnt vmcnt(7)
	v_pk_mul_f32 v[36:37], v[156:157], v[156:157]
	v_pk_mul_f32 v[38:39], v[158:159], v[158:159]
	v_add_f32_e32 v7, v36, v37
	v_add_f32_e32 v7, v7, v38
	v_add_f32_e32 v7, v7, v39
	v_add_f32_e32 v2, v2, v7
	ds_bpermute_b32 v7, v106, v2
	v_bfe_u32 v9, v159, 16, 1
	v_bfe_u32 v11, v158, 16, 1
	v_bfe_u32 v13, v157, 16, 1
	v_bfe_u32 v15, v156, 16, 1
	s_waitcnt lgkmcnt(0)
	v_add_f32_e32 v2, v2, v7
	ds_bpermute_b32 v7, v107, v2
	v_add3_u32 v15, v156, v15, s26
	v_add3_u32 v13, v157, v13, s26
	v_add3_u32 v11, v158, v11, s26
	v_add3_u32 v9, v159, v9, s26
	s_waitcnt lgkmcnt(0)
	v_add_f32_e32 v2, v2, v7
	ds_bpermute_b32 v7, v108, v2
	v_perm_b32 v37, v9, v11, s27
	v_perm_b32 v36, v13, v15, s27
	global_store_dwordx2 v[34:35], v[36:37], off
	s_waitcnt lgkmcnt(0)
	v_add_f32_e32 v2, v2, v7
	ds_bpermute_b32 v7, v109, v2
	s_waitcnt lgkmcnt(0)
	v_add_f32_e32 v2, v2, v7
	ds_bpermute_b32 v7, v110, v2
	s_waitcnt lgkmcnt(0)
	v_add_f32_e32 v2, v2, v7
	ds_bpermute_b32 v7, v111, v2
	s_and_saveexec_b64 s[4:5], s[0:1]
	s_cbranch_execz .LBB0_32
	v_lshlrev_b64 v[32:33], 7, v[32:33]
	s_waitcnt lgkmcnt(0)
	v_add_f32_e32 v2, v2, v7
	v_lshl_add_u64 v[32:33], v[4:5], 0, v[32:33]
	v_cndmask_b32_e64 v2, 0, v2, s[2:3]
	global_store_dword v[32:33], v2, off
